# prep0 conversion tiles moved to the workgroups without a GEMV task; conv GLU loads as in-place dwordx2; removed early wait before them
# speedup vs baseline: 1.0503x; 1.0039x over previous
.LBB0_443:
	v_mov_b32_e32 v122, v229
	v_readlane_b32 s40, v254, 30
	v_add_u32_e32 v0, s81, v122
	s_waitcnt lgkmcnt(0)
	v_ashrrev_i32_e32 v1, 31, v0
	v_readlane_b32 s46, v254, 36
	v_readlane_b32 s47, v254, 37
	v_and_b32_e32 v123, 63, v122
	v_readlane_b32 s48, v254, 38
	v_lshl_add_u64 v[2:3], v[0:1], 2, s[46:47]
	global_load_dword v108, v[2:3], off
	v_add_u32_e32 v2, 0x100, v0
	v_ashrrev_i32_e32 v3, 31, v2
	v_lshl_add_u64 v[2:3], v[2:3], 2, s[46:47]
	global_load_dword v107, v[2:3], off
	v_add_u32_e32 v2, 0x200, v0
	v_ashrrev_i32_e32 v3, 31, v2
	v_lshl_add_u64 v[2:3], v[2:3], 2, s[46:47]
	global_load_dword v106, v[2:3], off
	v_add_u32_e32 v2, 0x300, v0
	v_ashrrev_i32_e32 v3, 31, v2
	v_lshl_add_u64 v[2:3], v[2:3], 2, s[46:47]
	global_load_dword v103, v[2:3], off
	v_add_u32_e32 v2, 0x400, v0
	v_ashrrev_i32_e32 v3, 31, v2
	v_lshl_add_u64 v[2:3], v[2:3], 2, s[46:47]
	global_load_dword v101, v[2:3], off
	v_add_u32_e32 v2, 0x500, v0
	v_ashrrev_i32_e32 v3, 31, v2
	v_lshl_add_u64 v[2:3], v[2:3], 2, s[46:47]
	global_load_dword v100, v[2:3], off
	v_add_u32_e32 v2, 0x600, v0
	v_ashrrev_i32_e32 v3, 31, v2
	v_lshl_add_u64 v[2:3], v[2:3], 2, s[46:47]
	global_load_dword v99, v[2:3], off
	v_add_u32_e32 v2, 0x700, v0
	v_ashrrev_i32_e32 v3, 31, v2
	v_lshl_add_u64 v[2:3], v[2:3], 2, s[46:47]
	global_load_dword v98, v[2:3], off
	v_add_u32_e32 v2, 0x800, v0
	v_ashrrev_i32_e32 v3, 31, v2
	v_lshl_add_u64 v[2:3], v[2:3], 2, s[46:47]
	global_load_dword v97, v[2:3], off
	v_add_u32_e32 v2, 0x900, v0
	v_ashrrev_i32_e32 v3, 31, v2
	v_lshl_add_u64 v[2:3], v[2:3], 2, s[46:47]
	global_load_dword v96, v[2:3], off
	v_add_u32_e32 v2, 0xa00, v0
	v_ashrrev_i32_e32 v3, 31, v2
	v_lshl_add_u64 v[2:3], v[2:3], 2, s[46:47]
	global_load_dword v95, v[2:3], off
	v_add_u32_e32 v2, 0xb00, v0
	v_ashrrev_i32_e32 v3, 31, v2
	v_lshl_add_u64 v[2:3], v[2:3], 2, s[46:47]
	global_load_dword v94, v[2:3], off
	v_add_u32_e32 v2, 0xc00, v0
	v_ashrrev_i32_e32 v3, 31, v2
	v_lshl_add_u64 v[2:3], v[2:3], 2, s[46:47]
	global_load_dword v93, v[2:3], off
	v_add_u32_e32 v2, 0xd00, v0
	v_ashrrev_i32_e32 v3, 31, v2
	v_lshl_add_u64 v[2:3], v[2:3], 2, s[46:47]
	global_load_dword v92, v[2:3], off
	v_add_u32_e32 v2, 0xe00, v0
	v_ashrrev_i32_e32 v3, 31, v2
	v_lshl_add_u64 v[2:3], v[2:3], 2, s[46:47]
	global_load_dword v91, v[2:3], off
	v_add_u32_e32 v2, 0xf00, v0
	v_ashrrev_i32_e32 v3, 31, v2
	v_lshl_add_u64 v[2:3], v[2:3], 2, s[46:47]
	global_load_dword v90, v[2:3], off
	v_add_u32_e32 v2, 0x1000, v0
	v_ashrrev_i32_e32 v3, 31, v2
	v_lshl_add_u64 v[2:3], v[2:3], 2, s[46:47]
	global_load_dword v89, v[2:3], off
	v_add_u32_e32 v2, 0x1100, v0
	v_ashrrev_i32_e32 v3, 31, v2
	v_lshl_add_u64 v[2:3], v[2:3], 2, s[46:47]
	global_load_dword v88, v[2:3], off
	v_add_u32_e32 v2, 0x1200, v0
	v_ashrrev_i32_e32 v3, 31, v2
	v_lshl_add_u64 v[2:3], v[2:3], 2, s[46:47]
	global_load_dword v87, v[2:3], off
	v_add_u32_e32 v2, 0x1300, v0
	v_ashrrev_i32_e32 v3, 31, v2
	v_lshl_add_u64 v[2:3], v[2:3], 2, s[46:47]
	global_load_dword v86, v[2:3], off
	v_add_u32_e32 v2, 0x1400, v0
	v_ashrrev_i32_e32 v3, 31, v2
	v_lshl_add_u64 v[2:3], v[2:3], 2, s[46:47]
	global_load_dword v85, v[2:3], off
	v_add_u32_e32 v2, 0x1500, v0
	v_ashrrev_i32_e32 v3, 31, v2
	v_lshl_add_u64 v[2:3], v[2:3], 2, s[46:47]
	global_load_dword v84, v[2:3], off
	v_add_u32_e32 v2, 0x1600, v0
	v_ashrrev_i32_e32 v3, 31, v2
	v_lshl_add_u64 v[2:3], v[2:3], 2, s[46:47]
	global_load_dword v83, v[2:3], off
	v_add_u32_e32 v2, 0x1700, v0
	v_ashrrev_i32_e32 v3, 31, v2
	v_lshl_add_u64 v[2:3], v[2:3], 2, s[46:47]
	global_load_dword v82, v[2:3], off
	v_add_u32_e32 v2, 0x1800, v0
	v_ashrrev_i32_e32 v3, 31, v2
	v_lshl_add_u64 v[2:3], v[2:3], 2, s[46:47]
	global_load_dword v81, v[2:3], off
	v_add_u32_e32 v2, 0x1900, v0
	v_ashrrev_i32_e32 v3, 31, v2
	v_lshl_add_u64 v[2:3], v[2:3], 2, s[46:47]
	global_load_dword v80, v[2:3], off
	v_add_u32_e32 v2, 0x1a00, v0
	v_ashrrev_i32_e32 v3, 31, v2
	v_lshl_add_u64 v[2:3], v[2:3], 2, s[46:47]
	global_load_dword v79, v[2:3], off
	v_add_u32_e32 v2, 0x1b00, v0
	v_ashrrev_i32_e32 v3, 31, v2
	v_lshl_add_u64 v[2:3], v[2:3], 2, s[46:47]
	global_load_dword v78, v[2:3], off
	v_add_u32_e32 v2, 0x1c00, v0
	v_ashrrev_i32_e32 v3, 31, v2
	v_lshl_add_u64 v[2:3], v[2:3], 2, s[46:47]
	global_load_dword v77, v[2:3], off
	v_add_u32_e32 v2, 0x1d00, v0
	v_add_u32_e32 v0, 0x1e00, v0
	v_ashrrev_i32_e32 v3, 31, v2
	v_ashrrev_i32_e32 v1, 31, v0
	v_lshl_add_u64 v[2:3], v[2:3], 2, s[46:47]
	v_lshl_add_u64 v[0:1], v[0:1], 2, s[46:47]
	global_load_dword v76, v[2:3], off
	global_load_dword v74, v[0:1], off
	v_add_u32_e32 v0, s76, v122
	v_readlane_b32 s49, v254, 39
	v_ashrrev_i32_e32 v1, 31, v0
	v_lshlrev_b32_e32 v4, 4, v123
	v_lshl_add_u64 v[0:1], v[0:1], 2, s[48:49]
	global_load_dword v75, v[0:1], off
	s_nop 0
	global_load_dwordx4 v[0:3], v4, s[82:83]
	s_nop 0
	global_load_dwordx4 v[4:7], v4, s[84:85]
	s_add_i32 s94, s33, s90
	s_cmpk_lt_i32 s94, 0x80
	s_mov_b32 s0, 0x7ffffc00
	s_cselect_b32 s1, 0xffffff00, s0
	s_movk_i32 s0, 0x400
	s_cselect_b32 s0, 0x100, s0
	s_lshl_b32 s2, s94, 5
	v_ashrrev_i32_e32 v124, 6, v122
	s_and_b32 s3, s1, s2
	v_lshlrev_b32_e32 v104, 3, v123
	v_mov_b32_e32 v105, v201
	v_readlane_b32 s41, v254, 31
	v_lshlrev_b32_e32 v102, 2, v123
	s_add_i32 s29, s2, -15
	s_add_i32 s28, s3, s0
	v_lshl_add_u64 v[18:19], s[20:21], 0, v[104:105]
	v_cmp_gt_i32_e32 vcc, 62, v124
	v_mov_b32_e32 v8, 0
	v_mov_b32_e32 v10, 0
	v_mov_b32_e32 v11, 0
	v_mov_b32_e32 v12, 0
	v_mov_b32_e32 v13, 0
	v_mov_b32_e32 v109, 0
	v_mov_b32_e32 v110, 0
	v_mov_b32_e32 v111, 0
	v_mov_b32_e32 v112, 0
	v_readlane_b32 s42, v254, 32
	v_readlane_b32 s43, v254, 33
	v_readlane_b32 s44, v254, 34
	v_readlane_b32 s45, v254, 35
	v_readlane_b32 s50, v254, 40
	v_readlane_b32 s51, v254, 41
	v_readlane_b32 s52, v254, 42
	v_readlane_b32 s53, v254, 43
	v_readlane_b32 s54, v254, 44
	v_readlane_b32 s55, v254, 45
	s_mov_b64 s[96:97], exec
	v_lshlrev_b32_e32 v200, 1, v102
	v_add_u32_e32 v194, s29, v124
	v_cmp_le_i32_e64 s[0:1], s3, v194
	v_cmp_gt_i32_e64 s[72:73], s28, v194
	v_mov_b32_e32 v10, 0
	v_mov_b32_e32 v11, 0
	v_mov_b32_e32 v110, 0
	v_mov_b32_e32 v111, 0
	s_and_b64 s[0:1], s[0:1], s[72:73]
	s_and_b64 s[0:1], s[0:1], vcc
	s_and_b64 exec, s[96:97], s[0:1]
	s_cbranch_execz .Lglu_skip0
	v_mad_i64_i32 v[192:193], s[72:73], v194, s92, v[18:19]
	global_load_dwordx2 v[10:11], v[192:193], off
	global_load_dwordx2 v[110:111], v[192:193], off offset:512
.Lglu_skip0:
	s_mov_b64 exec, s[96:97]
	v_add_u32_e32 v105, 4, v124
	v_cmp_gt_i32_e64 s[38:39], 58, v124
	v_add_u32_e32 v194, s29, v105
	v_cmp_le_i32_e64 s[0:1], s3, v194
	v_cmp_gt_i32_e64 s[72:73], s28, v194
	v_mov_b32_e32 v8, 0
	v_mov_b32_e32 v9, 0
	v_mov_b32_e32 v114, 0
	v_mov_b32_e32 v115, 0
	s_and_b64 s[0:1], s[0:1], s[72:73]
	s_and_b64 s[0:1], s[0:1], s[38:39]
	s_and_b64 exec, s[96:97], s[0:1]
	s_cbranch_execz .Lglu_skip1
	v_mad_i64_i32 v[192:193], s[72:73], v194, s92, v[18:19]
	global_load_dwordx2 v[8:9], v[192:193], off
	global_load_dwordx2 v[114:115], v[192:193], off offset:512
.Lglu_skip1:
	s_mov_b64 exec, s[96:97]
	v_add_u32_e32 v113, 8, v124
	v_cmp_gt_i32_e64 s[40:41], 54, v124
	v_add_u32_e32 v194, s29, v113
	v_cmp_le_i32_e64 s[0:1], s3, v194
	v_cmp_gt_i32_e64 s[72:73], s28, v194
	v_mov_b32_e32 v20, 0
	v_mov_b32_e32 v21, 0
	v_mov_b32_e32 v120, 0
	v_mov_b32_e32 v121, 0
	s_and_b64 s[0:1], s[0:1], s[72:73]
	s_and_b64 s[0:1], s[0:1], s[40:41]
	s_and_b64 exec, s[96:97], s[0:1]
	s_cbranch_execz .Lglu_skip2
	v_mad_i64_i32 v[192:193], s[72:73], v194, s92, v[18:19]
	global_load_dwordx2 v[20:21], v[192:193], off
	global_load_dwordx2 v[120:121], v[192:193], off offset:512
.Lglu_skip2:
	s_mov_b64 exec, s[96:97]
	v_add_u32_e32 v118, 12, v124
	v_cmp_gt_i32_e64 s[42:43], 50, v124
	v_add_u32_e32 v194, s29, v118
	v_cmp_le_i32_e64 s[0:1], s3, v194
	v_cmp_gt_i32_e64 s[72:73], s28, v194
	v_mov_b32_e32 v14, 0
	v_mov_b32_e32 v15, 0
	v_mov_b32_e32 v128, 0
	v_mov_b32_e32 v129, 0
	s_and_b64 s[0:1], s[0:1], s[72:73]
	s_and_b64 s[0:1], s[0:1], s[42:43]
	s_and_b64 exec, s[96:97], s[0:1]
	s_cbranch_execz .Lglu_skip3
	v_mad_i64_i32 v[192:193], s[72:73], v194, s92, v[18:19]
	global_load_dwordx2 v[14:15], v[192:193], off
	global_load_dwordx2 v[128:129], v[192:193], off offset:512
.Lglu_skip3:
	s_mov_b64 exec, s[96:97]
	v_add_u32_e32 v126, 16, v124
	v_cmp_gt_i32_e64 s[44:45], 46, v124
	v_add_u32_e32 v194, s29, v126
	v_cmp_le_i32_e64 s[0:1], s3, v194
	v_cmp_gt_i32_e64 s[72:73], s28, v194
	v_mov_b32_e32 v28, 0
	v_mov_b32_e32 v29, 0
	v_mov_b32_e32 v132, 0
	v_mov_b32_e32 v133, 0
	s_and_b64 s[0:1], s[0:1], s[72:73]
	s_and_b64 s[0:1], s[0:1], s[44:45]
	s_and_b64 exec, s[96:97], s[0:1]
	s_cbranch_execz .Lglu_skip4
	v_mad_i64_i32 v[192:193], s[72:73], v194, s92, v[18:19]
	global_load_dwordx2 v[28:29], v[192:193], off
	global_load_dwordx2 v[132:133], v[192:193], off offset:512
.Lglu_skip4:
	s_mov_b64 exec, s[96:97]
	v_add_u32_e32 v131, 20, v124
	v_cmp_gt_i32_e64 s[46:47], 42, v124
	v_add_u32_e32 v194, s29, v131
	v_cmp_le_i32_e64 s[0:1], s3, v194
	v_cmp_gt_i32_e64 s[72:73], s28, v194
	v_mov_b32_e32 v24, 0
	v_mov_b32_e32 v25, 0
	v_mov_b32_e32 v138, 0
	v_mov_b32_e32 v139, 0
	s_and_b64 s[0:1], s[0:1], s[72:73]
	s_and_b64 s[0:1], s[0:1], s[46:47]
	s_and_b64 exec, s[96:97], s[0:1]
	s_cbranch_execz .Lglu_skip5
	v_mad_i64_i32 v[192:193], s[72:73], v194, s92, v[18:19]
	global_load_dwordx2 v[24:25], v[192:193], off
	global_load_dwordx2 v[138:139], v[192:193], off offset:512
.Lglu_skip5:
	s_mov_b64 exec, s[96:97]
	v_add_u32_e32 v136, 24, v124
	v_cmp_gt_i32_e64 s[48:49], 38, v124
	v_add_u32_e32 v194, s29, v136
	v_cmp_le_i32_e64 s[0:1], s3, v194
	v_cmp_gt_i32_e64 s[72:73], s28, v194
	v_mov_b32_e32 v36, 0
	v_mov_b32_e32 v37, 0
	v_mov_b32_e32 v142, 0
	v_mov_b32_e32 v143, 0
	s_and_b64 s[0:1], s[0:1], s[72:73]
	s_and_b64 s[0:1], s[0:1], s[48:49]
	s_and_b64 exec, s[96:97], s[0:1]
	s_cbranch_execz .Lglu_skip6
	v_mad_i64_i32 v[192:193], s[72:73], v194, s92, v[18:19]
	global_load_dwordx2 v[36:37], v[192:193], off
	global_load_dwordx2 v[142:143], v[192:193], off offset:512
.Lglu_skip6:
	s_mov_b64 exec, s[96:97]
	v_add_u32_e32 v141, 28, v124
	v_cmp_gt_i32_e64 s[50:51], 34, v124
	v_add_u32_e32 v194, s29, v141
	v_cmp_le_i32_e64 s[0:1], s3, v194
	v_cmp_gt_i32_e64 s[72:73], s28, v194
	v_mov_b32_e32 v32, 0
	v_mov_b32_e32 v33, 0
	v_mov_b32_e32 v148, 0
	v_mov_b32_e32 v149, 0
	s_and_b64 s[0:1], s[0:1], s[72:73]
	s_and_b64 s[0:1], s[0:1], s[50:51]
	s_and_b64 exec, s[96:97], s[0:1]
	s_cbranch_execz .Lglu_skip7
	v_mad_i64_i32 v[192:193], s[72:73], v194, s92, v[18:19]
	global_load_dwordx2 v[32:33], v[192:193], off
	global_load_dwordx2 v[148:149], v[192:193], off offset:512
.Lglu_skip7:
	s_mov_b64 exec, s[96:97]
	v_add_u32_e32 v146, 32, v124
	v_cmp_gt_i32_e64 s[52:53], 30, v124
	v_add_u32_e32 v194, s29, v146
	v_cmp_le_i32_e64 s[0:1], s3, v194
	v_cmp_gt_i32_e64 s[72:73], s28, v194
	v_mov_b32_e32 v44, 0
	v_mov_b32_e32 v45, 0
	v_mov_b32_e32 v152, 0
	v_mov_b32_e32 v153, 0
	s_and_b64 s[0:1], s[0:1], s[72:73]
	s_and_b64 s[0:1], s[0:1], s[52:53]
	s_and_b64 exec, s[96:97], s[0:1]
	s_cbranch_execz .Lglu_skip8
	v_mad_i64_i32 v[192:193], s[72:73], v194, s92, v[18:19]
	global_load_dwordx2 v[44:45], v[192:193], off
	global_load_dwordx2 v[152:153], v[192:193], off offset:512
.Lglu_skip8:
	s_mov_b64 exec, s[96:97]
	v_add_u32_e32 v151, 36, v124
	v_cmp_gt_i32_e64 s[54:55], 26, v124
	v_add_u32_e32 v194, s29, v151
	v_cmp_le_i32_e64 s[0:1], s3, v194
	v_cmp_gt_i32_e64 s[72:73], s28, v194
	v_mov_b32_e32 v40, 0
	v_mov_b32_e32 v41, 0
	v_mov_b32_e32 v158, 0
	v_mov_b32_e32 v159, 0
	s_and_b64 s[0:1], s[0:1], s[72:73]
	s_and_b64 s[0:1], s[0:1], s[54:55]
	s_and_b64 exec, s[96:97], s[0:1]
	s_cbranch_execz .Lglu_skip9
	v_mad_i64_i32 v[192:193], s[72:73], v194, s92, v[18:19]
	global_load_dwordx2 v[40:41], v[192:193], off
	global_load_dwordx2 v[158:159], v[192:193], off offset:512
.Lglu_skip9:
	s_mov_b64 exec, s[96:97]
	v_add_u32_e32 v156, 40, v124
	v_cmp_gt_i32_e64 s[56:57], 22, v124
	v_add_u32_e32 v194, s29, v156
	v_cmp_le_i32_e64 s[0:1], s3, v194
	v_cmp_gt_i32_e64 s[72:73], s28, v194
	v_mov_b32_e32 v52, 0
	v_mov_b32_e32 v53, 0
	v_mov_b32_e32 v162, 0
	v_mov_b32_e32 v163, 0
	s_and_b64 s[0:1], s[0:1], s[72:73]
	s_and_b64 s[0:1], s[0:1], s[56:57]
	s_and_b64 exec, s[96:97], s[0:1]
	s_cbranch_execz .Lglu_skip10
	v_mad_i64_i32 v[192:193], s[72:73], v194, s92, v[18:19]
	global_load_dwordx2 v[52:53], v[192:193], off
	global_load_dwordx2 v[162:163], v[192:193], off offset:512
.Lglu_skip10:
	s_mov_b64 exec, s[96:97]
	v_add_u32_e32 v161, 44, v124
	v_cmp_gt_i32_e64 s[58:59], 18, v124
	v_add_u32_e32 v194, s29, v161
	v_cmp_le_i32_e64 s[0:1], s3, v194
	v_cmp_gt_i32_e64 s[72:73], s28, v194
	v_mov_b32_e32 v48, 0
	v_mov_b32_e32 v49, 0
	v_mov_b32_e32 v168, 0
	v_mov_b32_e32 v169, 0
	s_and_b64 s[0:1], s[0:1], s[72:73]
	s_and_b64 s[0:1], s[0:1], s[58:59]
	s_and_b64 exec, s[96:97], s[0:1]
	s_cbranch_execz .Lglu_skip11
	v_mad_i64_i32 v[192:193], s[72:73], v194, s92, v[18:19]
	global_load_dwordx2 v[48:49], v[192:193], off
	global_load_dwordx2 v[168:169], v[192:193], off offset:512
.Lglu_skip11:
	s_mov_b64 exec, s[96:97]
	v_add_u32_e32 v166, 48, v124
	v_cmp_gt_i32_e64 s[60:61], 14, v124
	v_add_u32_e32 v194, s29, v166
	v_cmp_le_i32_e64 s[0:1], s3, v194
	v_cmp_gt_i32_e64 s[72:73], s28, v194
	v_mov_b32_e32 v60, 0
	v_mov_b32_e32 v61, 0
	v_mov_b32_e32 v172, 0
	v_mov_b32_e32 v173, 0
	s_and_b64 s[0:1], s[0:1], s[72:73]
	s_and_b64 s[0:1], s[0:1], s[60:61]
	s_and_b64 exec, s[96:97], s[0:1]
	s_cbranch_execz .Lglu_skip12
	v_mad_i64_i32 v[192:193], s[72:73], v194, s92, v[18:19]
	global_load_dwordx2 v[60:61], v[192:193], off
	global_load_dwordx2 v[172:173], v[192:193], off offset:512
.Lglu_skip12:
	s_mov_b64 exec, s[96:97]
	v_add_u32_e32 v171, 52, v124
	v_cmp_gt_i32_e64 s[62:63], 10, v124
	v_add_u32_e32 v194, s29, v171
	v_cmp_le_i32_e64 s[0:1], s3, v194
	v_cmp_gt_i32_e64 s[72:73], s28, v194
	v_mov_b32_e32 v56, 0
	v_mov_b32_e32 v57, 0
	v_mov_b32_e32 v178, 0
	v_mov_b32_e32 v179, 0
	s_and_b64 s[0:1], s[0:1], s[72:73]
	s_and_b64 s[0:1], s[0:1], s[62:63]
	s_and_b64 exec, s[96:97], s[0:1]
	s_cbranch_execz .Lglu_skip13
	v_mad_i64_i32 v[192:193], s[72:73], v194, s92, v[18:19]
	global_load_dwordx2 v[56:57], v[192:193], off
	global_load_dwordx2 v[178:179], v[192:193], off offset:512
.Lglu_skip13:
	s_mov_b64 exec, s[96:97]
	v_add_u32_e32 v176, 56, v124
	v_cmp_gt_i32_e64 s[64:65], 6, v124
	v_add_u32_e32 v194, s29, v176
	v_cmp_le_i32_e64 s[0:1], s3, v194
	v_cmp_gt_i32_e64 s[72:73], s28, v194
	v_mov_b32_e32 v68, 0
	v_mov_b32_e32 v69, 0
	v_mov_b32_e32 v182, 0
	v_mov_b32_e32 v183, 0
	s_and_b64 s[0:1], s[0:1], s[72:73]
	s_and_b64 s[0:1], s[0:1], s[64:65]
	s_and_b64 exec, s[96:97], s[0:1]
	s_cbranch_execz .Lglu_skip14
	v_mad_i64_i32 v[192:193], s[72:73], v194, s92, v[18:19]
	global_load_dwordx2 v[68:69], v[192:193], off
	global_load_dwordx2 v[182:183], v[192:193], off offset:512
.Lglu_skip14:
	s_mov_b64 exec, s[96:97]
	v_add_u32_e32 v181, 60, v124
	v_cmp_gt_i32_e64 s[66:67], 2, v124
	v_add_u32_e32 v194, s29, v181
	v_cmp_le_i32_e64 s[0:1], s3, v194
	v_cmp_gt_i32_e64 s[72:73], s28, v194
	v_mov_b32_e32 v64, 0
	v_mov_b32_e32 v65, 0
	v_mov_b32_e32 v186, 0
	v_mov_b32_e32 v187, 0
	s_and_b64 s[0:1], s[0:1], s[72:73]
	s_and_b64 s[0:1], s[0:1], s[66:67]
	s_and_b64 exec, s[96:97], s[0:1]
	s_cbranch_execz .Lglu_skip15
	v_mad_i64_i32 v[192:193], s[72:73], v194, s92, v[18:19]
	global_load_dwordx2 v[64:65], v[192:193], off
	global_load_dwordx2 v[186:187], v[192:193], off offset:512
.Lglu_skip15:
	s_mov_b64 exec, s[96:97]
	s_waitcnt vmcnt(0)
	v_lshlrev_b32_e32 v12, 16, v11
	v_and_b32_e32 v13, 0xffff0000, v11
	v_and_b32_e32 v11, 0xffff0000, v10
	v_lshlrev_b32_e32 v10, 16, v10
	v_lshlrev_b32_e32 v109, 16, v110
	v_and_b32_e32 v112, 0xffff0000, v111
	v_lshlrev_b32_e32 v111, 16, v111
	v_and_b32_e32 v110, 0xffff0000, v110
	v_lshlrev_b32_e32 v16, 16, v9
	v_and_b32_e32 v17, 0xffff0000, v9
	v_and_b32_e32 v9, 0xffff0000, v8
	v_lshlrev_b32_e32 v8, 16, v8
	v_lshlrev_b32_e32 v116, 16, v115
	v_and_b32_e32 v117, 0xffff0000, v115
	v_and_b32_e32 v115, 0xffff0000, v114
	v_lshlrev_b32_e32 v114, 16, v114
	v_lshlrev_b32_e32 v22, 16, v21
	v_and_b32_e32 v23, 0xffff0000, v21
	v_and_b32_e32 v21, 0xffff0000, v20
	v_lshlrev_b32_e32 v20, 16, v20
	v_lshlrev_b32_e32 v119, 16, v120
	v_and_b32_e32 v125, 0xffff0000, v121
	v_lshlrev_b32_e32 v121, 16, v121
	v_and_b32_e32 v120, 0xffff0000, v120
	v_lshlrev_b32_e32 v26, 16, v15
	v_and_b32_e32 v27, 0xffff0000, v15
	v_and_b32_e32 v15, 0xffff0000, v14
	v_lshlrev_b32_e32 v14, 16, v14
	v_lshlrev_b32_e32 v127, 16, v128
	v_and_b32_e32 v130, 0xffff0000, v129
	v_lshlrev_b32_e32 v129, 16, v129
	v_and_b32_e32 v128, 0xffff0000, v128
	v_lshlrev_b32_e32 v30, 16, v29
	v_and_b32_e32 v31, 0xffff0000, v29
	v_and_b32_e32 v29, 0xffff0000, v28
	v_lshlrev_b32_e32 v28, 16, v28
	v_lshlrev_b32_e32 v134, 16, v133
	v_and_b32_e32 v135, 0xffff0000, v133
	v_and_b32_e32 v133, 0xffff0000, v132
	v_lshlrev_b32_e32 v132, 16, v132
	v_lshlrev_b32_e32 v34, 16, v25
	v_and_b32_e32 v35, 0xffff0000, v25
	v_and_b32_e32 v25, 0xffff0000, v24
	v_lshlrev_b32_e32 v24, 16, v24
	v_lshlrev_b32_e32 v137, 16, v138
	v_and_b32_e32 v140, 0xffff0000, v139
	v_lshlrev_b32_e32 v139, 16, v139
	v_and_b32_e32 v138, 0xffff0000, v138
	v_lshlrev_b32_e32 v38, 16, v37
	v_and_b32_e32 v39, 0xffff0000, v37
	v_and_b32_e32 v37, 0xffff0000, v36
	v_lshlrev_b32_e32 v36, 16, v36
	v_lshlrev_b32_e32 v144, 16, v143
	v_and_b32_e32 v145, 0xffff0000, v143
	v_and_b32_e32 v143, 0xffff0000, v142
	v_lshlrev_b32_e32 v142, 16, v142
	v_lshlrev_b32_e32 v42, 16, v33
	v_and_b32_e32 v43, 0xffff0000, v33
	v_and_b32_e32 v33, 0xffff0000, v32
	v_lshlrev_b32_e32 v32, 16, v32
	v_lshlrev_b32_e32 v147, 16, v148
	v_and_b32_e32 v150, 0xffff0000, v149
	v_lshlrev_b32_e32 v149, 16, v149
	v_and_b32_e32 v148, 0xffff0000, v148
	v_lshlrev_b32_e32 v46, 16, v45
	v_and_b32_e32 v47, 0xffff0000, v45
	v_and_b32_e32 v45, 0xffff0000, v44
	v_lshlrev_b32_e32 v44, 16, v44
	v_lshlrev_b32_e32 v154, 16, v153
	v_and_b32_e32 v155, 0xffff0000, v153
	v_and_b32_e32 v153, 0xffff0000, v152
	v_lshlrev_b32_e32 v152, 16, v152
	v_lshlrev_b32_e32 v50, 16, v41
	v_and_b32_e32 v51, 0xffff0000, v41
	v_and_b32_e32 v41, 0xffff0000, v40
	v_lshlrev_b32_e32 v40, 16, v40
	v_lshlrev_b32_e32 v157, 16, v158
	v_and_b32_e32 v160, 0xffff0000, v159
	v_lshlrev_b32_e32 v159, 16, v159
	v_and_b32_e32 v158, 0xffff0000, v158
	v_lshlrev_b32_e32 v54, 16, v53
	v_and_b32_e32 v55, 0xffff0000, v53
	v_and_b32_e32 v53, 0xffff0000, v52
	v_lshlrev_b32_e32 v52, 16, v52
	v_lshlrev_b32_e32 v164, 16, v163
	v_and_b32_e32 v165, 0xffff0000, v163
	v_and_b32_e32 v163, 0xffff0000, v162
	v_lshlrev_b32_e32 v162, 16, v162
	v_lshlrev_b32_e32 v58, 16, v49
	v_and_b32_e32 v59, 0xffff0000, v49
	v_and_b32_e32 v49, 0xffff0000, v48
	v_lshlrev_b32_e32 v48, 16, v48
	v_lshlrev_b32_e32 v167, 16, v168
	v_and_b32_e32 v170, 0xffff0000, v169
	v_lshlrev_b32_e32 v169, 16, v169
	v_and_b32_e32 v168, 0xffff0000, v168
	v_lshlrev_b32_e32 v62, 16, v61
	v_and_b32_e32 v63, 0xffff0000, v61
	v_and_b32_e32 v61, 0xffff0000, v60
	v_lshlrev_b32_e32 v60, 16, v60
	v_lshlrev_b32_e32 v174, 16, v173
	v_and_b32_e32 v175, 0xffff0000, v173
	v_and_b32_e32 v173, 0xffff0000, v172
	v_lshlrev_b32_e32 v172, 16, v172
	v_lshlrev_b32_e32 v66, 16, v57
	v_and_b32_e32 v67, 0xffff0000, v57
	v_and_b32_e32 v57, 0xffff0000, v56
	v_lshlrev_b32_e32 v56, 16, v56
	v_lshlrev_b32_e32 v177, 16, v178
	v_and_b32_e32 v180, 0xffff0000, v179
	v_lshlrev_b32_e32 v179, 16, v179
	v_and_b32_e32 v178, 0xffff0000, v178
	v_lshlrev_b32_e32 v70, 16, v69
	v_and_b32_e32 v71, 0xffff0000, v69
	v_and_b32_e32 v69, 0xffff0000, v68
	v_lshlrev_b32_e32 v68, 16, v68
	v_lshlrev_b32_e32 v184, 16, v183
	v_and_b32_e32 v185, 0xffff0000, v183
	v_and_b32_e32 v183, 0xffff0000, v182
	v_lshlrev_b32_e32 v182, 16, v182
	v_lshlrev_b32_e32 v72, 16, v65
	v_and_b32_e32 v73, 0xffff0000, v65
	v_and_b32_e32 v65, 0xffff0000, v64
	v_lshlrev_b32_e32 v64, 16, v64
	v_lshlrev_b32_e32 v188, 16, v187
	v_and_b32_e32 v189, 0xffff0000, v187
	v_and_b32_e32 v187, 0xffff0000, v186
	v_lshlrev_b32_e32 v186, 16, v186
	s_or_b64 exec, exec, s[96:97]
	v_lshl_add_u32 v102, v102, 2, s69
	s_and_saveexec_b64 s[0:1], vcc
	s_cbranch_execnz .LBB0_540

.LBB0_871:
	v_readlane_b32 s0, v254, 23
	v_readlane_b32 s1, v255, 34
	s_nop 3
	s_cmp_ge_i32 s0, 64
	s_cbranch_scc0 .Lt0_old
	s_add_i32 s28, s1, 0xfffffe80
	s_cmp_lt_i32 s28, 0
	s_cselect_b32 s28, 0x2e8, s28
	s_mov_b32 s2, s0
	s_branch .Lt0_set
.Lt0_old:
	v_readlane_b32 s0, v254, 23
	v_readlane_b32 s1, v255, 34
	s_add_i32 s0, s0, s1
	s_ashr_i32 s1, s0, 31
	s_abs_i32 s0, s0
	v_readlane_b32 s2, v255, 14
	s_mul_hi_u32 s2, s0, s2
	v_readlane_b32 s3, v255, 13
	s_mul_i32 s2, s2, s3
	s_sub_i32 s0, s0, s2
	s_sub_i32 s2, s0, s3
	s_cmp_ge_u32 s0, s3
	s_cselect_b32 s0, s2, s0
	s_sub_i32 s2, s0, s3
	s_cmp_ge_u32 s0, s3
	s_cselect_b32 s0, s2, s0
	s_xor_b32 s0, s0, s1
	s_sub_i32 s28, s0, s1
	s_mov_b32 s2, s70
.Lt0_set:
	s_nop 3
	v_writelane_b32 v255, s2, 57
	s_nop 1
	v_mov_b32_e32 v16, v229
	s_cmpk_gt_i32 s28, 0x2e7
	s_cbranch_scc0 .LBB0_872
	s_getpc_b64 s[98:99]

.LBB0_884:
	v_ashrrev_i32_e32 v18, 4, v16
	v_add_u32_e32 v10, s36, v18
	v_ashrrev_i32_e32 v0, 31, v10
	v_mul_lo_u32 v2, s40, v0
	v_mul_lo_u32 v3, s41, v10
	s_waitcnt lgkmcnt(0)
	v_mad_u64_u32 v[0:1], s[42:43], s40, v10, 0
	v_add_u32_e32 v8, 32, v10
	v_add3_u32 v1, v1, v2, v3
	v_lshlrev_b32_e32 v2, 2, v16
	v_ashrrev_i32_e32 v9, 31, v8
	v_and_b32_e32 v24, 60, v2
	v_add_u32_e32 v2, 16, v10
	v_mul_lo_u32 v11, s40, v9
	v_mul_lo_u32 v12, s41, v8
	v_mad_u64_u32 v[8:9], s[44:45], s40, v8, 0
	v_add_u32_e32 v10, 48, v10
	v_ashrrev_i32_e32 v3, 31, v2
	v_add3_u32 v9, v9, v11, v12
	v_ashrrev_i32_e32 v11, 31, v10
	v_mul_lo_u32 v4, s40, v3
	v_mul_lo_u32 v5, s41, v2
	v_mad_u64_u32 v[2:3], s[44:45], s40, v2, 0
	v_mul_lo_u32 v12, s40, v11
	v_mul_lo_u32 v13, s41, v10
	v_mad_u64_u32 v[10:11], s[40:41], s40, v10, 0
	s_ashr_i32 s3, s2, 31
	v_add3_u32 v3, v3, v4, v5
	v_add3_u32 v11, v11, v12, v13
	v_lshl_add_u64 v[0:1], v[0:1], 2, s[38:39]
	s_lshl_b64 s[42:43], s[2:3], 2
	v_lshl_add_u64 v[2:3], v[2:3], 2, s[38:39]
	v_lshl_add_u64 v[8:9], v[8:9], 2, s[38:39]
	v_lshl_add_u64 v[10:11], v[10:11], 2, s[38:39]
	v_lshl_add_u64 v[0:1], v[0:1], 0, s[42:43]
	v_lshlrev_b32_e32 v200, 2, v24
	v_lshl_add_u64 v[2:3], v[2:3], 0, s[42:43]
	v_lshl_add_u64 v[8:9], v[8:9], 0, s[42:43]
	v_lshl_add_u64 v[10:11], v[10:11], 0, s[42:43]
	v_lshl_add_u64 v[0:1], v[0:1], 0, v[200:201]
	v_lshl_add_u64 v[2:3], v[2:3], 0, v[200:201]
	v_lshl_add_u64 v[8:9], v[8:9], 0, v[200:201]
	v_lshl_add_u64 v[10:11], v[10:11], 0, v[200:201]
	global_load_dwordx4 v[4:7], v[0:1], off
	s_nop 0
	global_load_dwordx4 v[0:3], v[2:3], off
	s_nop 0
	global_load_dwordx4 v[12:15], v[8:9], off
	s_nop 0
	global_load_dwordx4 v[8:11], v[10:11], off
	s_movk_i32 s3, 0x104
	v_mul_lo_u32 v17, v18, s3
	v_add3_u32 v19, s69, v17, v200
	v_lshlrev_b32_e32 v17, 3, v16
	v_and_b32_e32 v26, 56, v17
	v_ashrrev_i32_e32 v20, 3, v16
	v_mul_u32_u24_e32 v17, 0x41, v26
	v_add_u32_e32 v16, 0x100, v16
	v_lshl_add_u32 v17, v17, 2, s69
	v_ashrrev_i32_e32 v22, 3, v16
	v_readlane_b32 s30, v255, 57
	s_nop 3
	s_lshl_b32 s33, s30, 4
	s_lshl_b32 s30, s30, 6
	s_lshl_b32 s37, s28, 4
	v_lshl_add_u32 v21, v20, 2, v17
	v_lshl_add_u32 v23, v22, 2, v17
	s_lshl_b32 s3, s28, 6
	s_add_i32 s50, s33, s37
	v_mov_b32_e32 v17, 0
	v_lshlrev_b32_e32 v200, 2, v24
	v_lshlrev_b32_e32 v16, 1, v26
	s_mov_b32 s51, s30
	v_mov_b32_e32 v24, 0
	v_mov_b32_e32 v25, 0
	v_mov_b32_e32 v26, 0
	v_mov_b32_e32 v27, 0
	v_mov_b32_e32 v28, 0
	v_mov_b32_e32 v29, 0
	v_mov_b32_e32 v30, 0
	v_mov_b32_e32 v31, 0
	v_mov_b32_e32 v32, 0
	v_mov_b32_e32 v33, 0
	v_mov_b32_e32 v34, 0
	v_mov_b32_e32 v35, 0
	v_mov_b32_e32 v36, 0
	v_mov_b32_e32 v37, 0
	v_mov_b32_e32 v38, 0
	s_mov_b64 s[38:39], s[0:1]
	s_mov_b32 s52, s29
	s_branch .LBB0_887

.LBB0_887:
	s_waitcnt vmcnt(0)
	ds_write2_b32 v19, v4, v5 offset1:1
	ds_write2_b32 v19, v6, v7 offset0:2 offset1:3
	v_add_u32_e32 v4, 0x1040, v19
	ds_write2_b32 v4, v0, v1 offset1:1
	v_add_u32_e32 v0, 0x1048, v19
	ds_write2_b32 v0, v2, v3 offset1:1
	v_add_u32_e32 v0, 0x2080, v19
	ds_write2_b32 v0, v12, v13 offset1:1
	v_add_u32_e32 v0, 0x2088, v19
	ds_write2_b32 v0, v14, v15 offset1:1
	v_add_u32_e32 v0, 0x30c0, v19
	ds_write2_b32 v0, v8, v9 offset1:1
	v_add_u32_e32 v0, 0x30c8, v19
	ds_write2_b32 v0, v10, v11 offset1:1
	v_readlane_b32 s40, v255, 57
	s_nop 3
	s_add_i32 s28, s28, s40
	s_waitcnt lgkmcnt(0)
	s_barrier
	s_cmpk_gt_i32 s28, 0x2e7
	s_cselect_b64 s[40:41], -1, 0
	s_and_b64 vcc, exec, s[40:41]
	v_mov_b32_e32 v11, v38
	v_mov_b32_e32 v10, v37
	v_mov_b32_e32 v9, v36
	v_mov_b32_e32 v8, v35
	v_mov_b32_e32 v15, v34
	v_mov_b32_e32 v14, v33
	v_mov_b32_e32 v13, v32
	v_mov_b32_e32 v12, v31
	v_mov_b32_e32 v3, v30
	v_mov_b32_e32 v2, v29
	v_mov_b32_e32 v1, v28
	v_mov_b32_e32 v0, v27
	v_mov_b32_e32 v7, v26
	v_mov_b32_e32 v6, v25
	v_mov_b32_e32 v5, v24
	v_mov_b32_e32 v4, v17
	s_mov_b32 s53, s36
	s_mov_b32 s42, s2
	s_cbranch_vccnz .LBB0_886
	s_cmpk_gt_i32 s28, 0x2bf
	s_cbranch_scc0 .LBB0_898
	s_cmpk_gt_u32 s28, 0x2d3
	s_mov_b64 s[48:49], -1
	s_cbranch_scc0 .LBB0_894
	s_add_i32 s37, s28, 0xfffffd2c
	s_cmp_gt_u32 s37, 15
	s_mov_b64 s[42:43], -1
	s_cbranch_scc0 .LBB0_892
	s_add_i32 s94, s28, 0xfffffd20
	v_readlane_b32 s52, v253, 3
	s_lshl_b64 s[38:39], s[94:95], 14
	v_readlane_b32 s56, v253, 7
	v_readlane_b32 s53, v253, 4
	v_readlane_b32 s54, v253, 5
	v_readlane_b32 s55, v253, 6
	v_readlane_b32 s57, v253, 8
	v_readlane_b32 s58, v253, 9
	v_readlane_b32 s59, v253, 10
	v_readlane_b32 s60, v253, 11
	v_readlane_b32 s61, v253, 12
	v_readlane_b32 s62, v253, 13
	v_readlane_b32 s63, v253, 14
	v_readlane_b32 s64, v253, 15
	v_readlane_b32 s65, v253, 16
	v_readlane_b32 s66, v253, 17
	v_readlane_b32 s67, v253, 18
	s_add_u32 s44, s56, s38
	s_addc_u32 s45, s57, s39
	v_readlane_b32 s52, v254, 57
	s_lshl_b64 s[38:39], s[94:95], 13
	v_readlane_b32 s64, v255, 5
	v_readlane_b32 s65, v255, 6
	s_add_u32 s38, s64, s38
	s_mov_b32 s94, 0x800000
	v_readlane_b32 s53, v254, 58
	v_readlane_b32 s54, v254, 59
	v_readlane_b32 s55, v254, 60
	v_readlane_b32 s56, v254, 61
	v_readlane_b32 s57, v254, 62
	v_readlane_b32 s58, v254, 63
	v_readlane_b32 s59, v255, 0
	v_readlane_b32 s60, v255, 1
	v_readlane_b32 s61, v255, 2
	v_readlane_b32 s62, v255, 3
	v_readlane_b32 s63, v255, 4
	v_readlane_b32 s66, v255, 7
	v_readlane_b32 s67, v255, 8
	s_addc_u32 s39, s65, s39
	s_mov_b64 s[42:43], 0
